# static s_setprio 1 for waves 4-7 during the windowed-GQA attention units too (reset before the next phase)
# baseline (speedup 1.0000x reference)
; #define GSYNC() xcd_barrier(xb)
; __global__ void __launch_bounds__(NTHR) mega(Params p) {
;     ...
;   for (int grp = 0; grp < 3; ++grp) {
;     for (int l = 0; l < 2; ++l)
;       for (int ph = 2; ph <= 10; ++ph) { run_phase(p, grp, l, ph, lds); GSYNC(); }
.LBB0_447:
	s_setprio 0
	v_readlane_b32 s0, v248, 1
	v_readlane_b32 s1, v248, 2
	s_and_b64 vcc, exec, s[0:1]
	s_cbranch_vccz .LBB0_1812
	s_cmp_gt_i32 s86, 2
	s_mov_b64 s[0:1], -1
	s_cbranch_scc0 .LBB0_451
	v_readlane_b32 s0, v252, 40
	v_readlane_b32 s1, v252, 41
	v_readlane_b32 s34, v251, 58
	v_readlane_b32 s24, v251, 52
	s_andn2_b64 vcc, exec, s[0:1]
	v_readlane_b32 s35, v251, 59
	v_readlane_b32 s25, v251, 53
	v_readlane_b32 s2, v249, 26
	v_readlane_b32 s3, v249, 27
	s_cbranch_vccz .LBB0_479

; DEV void run_phase(const Params& p, const int grp, const int l, const int ph, char* lds) {
;     ...
;         for (int u = bid; u < nU; u += nblk) {
;           const int b = u & 255, i = u >> 8; const int y = b >> 3; const int qb = y % nqb, sub = y / nqb;
;           const int sh = (b & 7) + 8 * (i * (32 / nqb) + sub); const int s = sh >> 3, h = sh & 7, kvh = h >> 2;
;           const size_t tq = (size_t)s * seqlen + (size_t)qb * 256, tk = (size_t)s * seqlen;
;           const int q0 = qb * 256; const int kb0 = q0 - 128 < 0 ? 0 : q0 - 128; const int ke = q0 + 384 > seqlen ? seqlen : q0 + 384;
;     ...
;           attn_unit<128, true, true>(PROJ + tq * INP + C_Q + h * 128, INP, PROJ + tk * INP + C_K + kvh * 128, INP, PROJ + tk * INP + C_VV + kvh * 128, INP,
;                                PROJ + tq * INP + C_Q + h * 128, INP, kb0, (ke - kb0) / 64, q0, sinkp[h], 0.08838834764831845f, lds);
.LBB0_1779:
	s_bitcmp1_b32 s100, 0
	s_cbranch_scc0 .Lgqa_noprio
	s_setprio 1
